# v28 + push release: the last-arriving XCD leader bumps all 8 per-XCD generation words itself (one poll hop instead of two), per-leader generation bump removed
# speedup vs baseline: 1.0084x; 1.0007x over previous
.Lpush_0:
	s_or_b64 exec, exec, s[10:11]
	v_mov_b32_e32 v5, 1
	v_mov_b32_e32 v1, 0x2400
	global_atomic_add v1, v5, s[92:93]
	global_atomic_add v1, v5, s[92:93] offset:256
	global_atomic_add v1, v5, s[92:93] offset:512
	global_atomic_add v1, v5, s[92:93] offset:768
	global_atomic_add v1, v5, s[92:93] offset:1024
	global_atomic_add v1, v5, s[92:93] offset:1280
	global_atomic_add v1, v5, s[92:93] offset:1536
	global_atomic_add v1, v5, s[92:93] offset:1792
	v_mov_b64_e32 v[2:3], s[8:9]
	s_branch .LBB0_54

.LBB0_56:
	s_or_b64 exec, exec, s[8:9]
	s_mov_b64 s[8:9], exec
	v_mbcnt_lo_u32_b32 v1, s8, 0
	v_mbcnt_hi_u32_b32 v1, s9, v1
	v_cmp_eq_u32_e32 vcc, 0, v1
	s_waitcnt vmcnt(0)
	s_nop 0
	s_and_saveexec_b64 s[10:11], vcc
	s_cbranch_execz .LBB0_58
	s_bcnt1_i32_b64 s8, s[8:9]
	v_mov_b32_e32 v1, 0x2000
	v_mov_b32_e32 v2, s8
	s_nop 0

.Lpush_1:
	s_or_b64 exec, exec, s[8:9]
	v_mov_b32_e32 v5, 1
	v_mov_b32_e32 v1, 0x2400
	global_atomic_add v1, v5, s[92:93]
	global_atomic_add v1, v5, s[92:93] offset:256
	global_atomic_add v1, v5, s[92:93] offset:512
	global_atomic_add v1, v5, s[92:93] offset:768
	global_atomic_add v1, v5, s[92:93] offset:1024
	global_atomic_add v1, v5, s[92:93] offset:1280
	global_atomic_add v1, v5, s[92:93] offset:1536
	global_atomic_add v1, v5, s[92:93] offset:1792
	v_mov_b64_e32 v[2:3], s[6:7]
	s_branch .LBB0_196

.LBB0_198:
	s_or_b64 exec, exec, s[6:7]
	s_mov_b64 s[6:7], exec
	v_mbcnt_lo_u32_b32 v1, s6, 0
	v_mbcnt_hi_u32_b32 v1, s7, v1
	v_cmp_eq_u32_e32 vcc, 0, v1
	s_waitcnt vmcnt(0)
	s_nop 0
	s_and_saveexec_b64 s[8:9], vcc
	s_cbranch_execz .LBB0_200
	s_bcnt1_i32_b64 s6, s[6:7]
	v_mov_b32_e32 v1, 0x2000
	v_mov_b32_e32 v2, s6
	s_nop 0

.Lpush_2:
	s_or_b64 exec, exec, s[6:7]
	v_mov_b32_e32 v5, 1
	v_mov_b32_e32 v1, 0x2400
	global_atomic_add v1, v5, s[92:93]
	global_atomic_add v1, v5, s[92:93] offset:256
	global_atomic_add v1, v5, s[92:93] offset:512
	global_atomic_add v1, v5, s[92:93] offset:768
	global_atomic_add v1, v5, s[92:93] offset:1024
	global_atomic_add v1, v5, s[92:93] offset:1280
	global_atomic_add v1, v5, s[92:93] offset:1536
	global_atomic_add v1, v5, s[92:93] offset:1792
	v_mov_b64_e32 v[2:3], s[4:5]
	s_branch .LBB0_259

.LBB0_261:
	s_or_b64 exec, exec, s[4:5]
	s_mov_b64 s[4:5], exec
	v_mbcnt_lo_u32_b32 v1, s4, 0
	v_mbcnt_hi_u32_b32 v1, s5, v1
	v_cmp_eq_u32_e32 vcc, 0, v1
	s_waitcnt vmcnt(0)
	s_nop 0
	s_and_saveexec_b64 s[6:7], vcc
	s_cbranch_execz .LBB0_263
	s_bcnt1_i32_b64 s4, s[4:5]
	v_mov_b32_e32 v1, 0x2000
	v_mov_b32_e32 v2, s4
	s_nop 0

.Lpush_3:
	s_or_b64 exec, exec, s[8:9]
	v_mov_b32_e32 v3, 1
	v_mov_b32_e32 v2, 0x2400
	global_atomic_add v2, v3, s[92:93]
	global_atomic_add v2, v3, s[92:93] offset:256
	global_atomic_add v2, v3, s[92:93] offset:512
	global_atomic_add v2, v3, s[92:93] offset:768
	global_atomic_add v2, v3, s[92:93] offset:1024
	global_atomic_add v2, v3, s[92:93] offset:1280
	global_atomic_add v2, v3, s[92:93] offset:1536
	global_atomic_add v2, v3, s[92:93] offset:1792
	v_mov_b64_e32 v[2:3], s[6:7]
	s_branch .LBB0_441

.Lpush_4:
	s_or_b64 exec, exec, s[6:7]
	v_mov_b32_e32 v5, 1
	v_mov_b32_e32 v1, 0x2400
	global_atomic_add v1, v5, s[92:93]
	global_atomic_add v1, v5, s[92:93] offset:256
	global_atomic_add v1, v5, s[92:93] offset:512
	global_atomic_add v1, v5, s[92:93] offset:768
	global_atomic_add v1, v5, s[92:93] offset:1024
	global_atomic_add v1, v5, s[92:93] offset:1280
	global_atomic_add v1, v5, s[92:93] offset:1536
	global_atomic_add v1, v5, s[92:93] offset:1792
	v_mov_b64_e32 v[2:3], s[8:9]
	s_branch .LBB0_505

.Lpush_5:
	s_or_b64 exec, exec, s[4:5]
	v_mov_b32_e32 v5, 1
	v_mov_b32_e32 v1, 0x2400
	global_atomic_add v1, v5, s[92:93]
	global_atomic_add v1, v5, s[92:93] offset:256
	global_atomic_add v1, v5, s[92:93] offset:512
	global_atomic_add v1, v5, s[92:93] offset:768
	global_atomic_add v1, v5, s[92:93] offset:1024
	global_atomic_add v1, v5, s[92:93] offset:1280
	global_atomic_add v1, v5, s[92:93] offset:1536
	global_atomic_add v1, v5, s[92:93] offset:1792
	v_mov_b64_e32 v[2:3], s[6:7]
	s_branch .LBB0_629

.Lpush_9:
	s_or_b64 exec, exec, s[4:5]
	v_mov_b32_e32 v5, 1
	v_mov_b32_e32 v1, 0x2400
	global_atomic_add v1, v5, s[92:93]
	global_atomic_add v1, v5, s[92:93] offset:256
	global_atomic_add v1, v5, s[92:93] offset:512
	global_atomic_add v1, v5, s[92:93] offset:768
	global_atomic_add v1, v5, s[92:93] offset:1024
	global_atomic_add v1, v5, s[92:93] offset:1280
	global_atomic_add v1, v5, s[92:93] offset:1536
	global_atomic_add v1, v5, s[92:93] offset:1792
	v_mov_b64_e32 v[2:3], s[8:9]
	s_branch .LBB0_948

.LBB0_950:
	s_or_b64 exec, exec, s[4:5]
	s_mov_b64 s[4:5], exec
	v_mbcnt_lo_u32_b32 v1, s4, 0
	v_mbcnt_hi_u32_b32 v1, s5, v1
	v_cmp_eq_u32_e32 vcc, 0, v1
	s_waitcnt vmcnt(0)
	s_nop 0
	s_and_saveexec_b64 s[8:9], vcc
	s_cbranch_execz .LBB0_952
	s_bcnt1_i32_b64 s4, s[4:5]
	v_mov_b32_e32 v1, 0x2000
	v_mov_b32_e32 v2, s4
	s_nop 0
